# part of the W_up transposes moved onto the sample-path workgroups at the end of P3; LDS read batches capped at 15 outstanding
# speedup vs baseline: 1.0603x; 1.0023x over previous
; #define LAS __attribute__((address_space(3)))
; __device__ __forceinline__ int ltid() { int t = threadIdx.x; asm volatile("" : "+v"(t)); return t; }
; __device__ __forceinline__ KArgs ka_get() { KArgs p = (KArgs)__builtin_amdgcn_kernarg_segment_ptr(); asm volatile("" : "+s"(p)); return p; }
; __device__ __forceinline__ int win_dest_row(int n0) {
;     if (n0 < 5120) return n0;
;     if (n0 < 5152) return CDT + (n0 - 5120);
;     if (n0 < 7200) { const int c = n0 - 5152; return CCF + 256 * (c >> 7) + (c & 127); }
;     { const int c = n0 - 7200; return CCF + 256 * (c >> 7) + 128 + (c & 127); }
; }
; __global__ void __launch_bounds__(512, 2) mk_fwd(Args args) {
;     ...
;     if (IN(0)) { const KArgs KA = ka_get(); const int tid = ltid(), lane = tid & 63, wave = __builtin_amdgcn_readfirstlane(tid >> 6); (void)lane; (void)wave;
;         LAS float* scr = (LAS float*)(lds + wave * 16384);
;         const int gw = bx * 8 + wave, NGW = G * 8;
;         constexpr int I_IN = (DM / 64) * (9248 / 32), I_OUT = (DMIX / 64) * (DM / 32), I_UP = (DM / 64) * (FF2 / 32), I_DN = (FF / 64) * (DM / 32);
;         constexpr int n_items0 = I_IN + I_OUT + I_UP + I_DN;
;         for (int it = gw; it < n_items0; it += NGW) {
;             int r = it;
;             if (r < I_IN) { const int nblk = 9248 / 32, kb = r / nblk, nb = r % nblk; p0_transpose_item(w_in, DM, 9248, WinT, 64 * kb, 32 * nb, win_dest_row(32 * nb), scr, lane); continue; } r -= I_IN;
.LBB0_18:
	s_cmp_lt_i32 s88, 1
	s_cselect_b64 s[0:1], -1, 0
	s_cmp_gt_i32 s89, 0
	s_cselect_b64 s[4:5], -1, 0
	s_and_b64 s[0:1], s[0:1], s[4:5]
	s_andn2_b64 vcc, exec, s[0:1]
	s_cbranch_vccnz .LBB0_61
	s_mov_b64 s[8:9], s[96:97]
	v_mov_b32_e32 v1, v212
	s_lshl_b32 s10, s94, 3
	v_readfirstlane_b32 s3, v1
	s_ashr_i32 s4, s3, 6
	s_lshl_b32 s3, s2, 3
	v_and_b32_e32 v3, 63, v1
	s_add_i32 s3, s4, s3
	s_cmpk_gt_i32 s3, 0x382f
	v_lshlrev_b32_e32 v0, 3, v3
	s_cbranch_scc1 .LBB0_54
	s_load_dwordx2 s[12:13], s[8:9], 0x38
	s_load_dwordx2 s[14:15], s[8:9], 0x90
	s_load_dwordx2 s[16:17], s[8:9], 0xa0
	s_load_dwordx2 s[18:19], s[8:9], 0xb8
	s_load_dwordx2 s[20:21], s[8:9], 0x98
	s_load_dwordx2 s[22:23], s[8:9], 0xd0
	v_lshrrev_b32_e32 v4, 3, v3
	v_and_b32_e32 v7, 7, v3
	v_lshlrev_b32_e32 v5, 4, v7
	v_lshlrev_b32_e32 v6, 5, v7
	s_lshl_b32 s24, s4, 14
	v_lshl_add_u32 v16, v4, 7, s24
	v_xor_b32_e32 v8, 0, v7
	v_lshl_add_u32 v8, v8, 4, v16
	v_xor_b32_e32 v9, 1, v7
	v_lshl_add_u32 v9, v9, 4, v16
	v_xor_b32_e32 v10, 2, v7
	v_lshl_add_u32 v10, v10, 4, v16
	v_xor_b32_e32 v11, 3, v7
	v_lshl_add_u32 v11, v11, 4, v16
	v_xor_b32_e32 v12, 4, v7
	v_lshl_add_u32 v12, v12, 4, v16
	v_xor_b32_e32 v13, 5, v7
	v_lshl_add_u32 v13, v13, 4, v16
	v_xor_b32_e32 v14, 6, v7
	v_lshl_add_u32 v14, v14, 4, v16
	v_xor_b32_e32 v15, 7, v7
	v_lshl_add_u32 v15, v15, 4, v16
	v_lshlrev_b32_e32 v20, 2, v7
	v_lshl_add_u32 v21, v7, 10, s24
	v_add_u32_e32 v16, 0, v4
	v_xor_b32_e32 v16, v16, v20
	v_lshl_add_u32 v16, v16, 2, v21
	v_add_u32_e32 v17, 8, v4
	v_xor_b32_e32 v17, v17, v20
	v_lshl_add_u32 v17, v17, 2, v21
	v_add_u32_e32 v18, 16, v4
	v_xor_b32_e32 v18, v18, v20
	v_lshl_add_u32 v18, v18, 2, v21
	v_add_u32_e32 v19, 24, v4
	v_xor_b32_e32 v19, v19, v20
	v_lshl_add_u32 v19, v19, 2, v21
	s_mov_b32 s11, s3
	s_waitcnt lgkmcnt(0)
	s_cmpk_lt_u32 s11, 9248
	s_cbranch_scc0 .Lp0t_pro_notin
	s_mul_hi_u32 s40, s11, 14861479
	s_mul_i32 s42, s40, 289
	s_sub_u32 s41, s11, s42
	s_mul_i32 s42, s40, 2367488
	s_lshl_b32 s43, s41, 7
	s_add_u32 s42, s42, s43
	s_add_u32 s26, s12, s42
	s_addc_u32 s27, s13, 0
	s_mov_b32 s28, 36992
	s_lshl_b32 s45, s41, 5
	s_mov_b32 s46, s45
	s_cmpk_lt_u32 s45, 5120
	s_cbranch_scc1 .Lp0t_pro_drow_done
	s_movk_i32 s46, 9216
	s_cmpk_lt_u32 s45, 5152
	s_cbranch_scc1 .Lp0t_pro_drow_done
	s_sub_u32 s47, s45, 5152
	s_movk_i32 s43, 5120
	s_cmpk_lt_u32 s45, 7200
	s_cbranch_scc1 .Lp0t_pro_drow_cf
	s_sub_u32 s47, s45, 7200
	s_movk_i32 s43, 5248

; __device__ __forceinline__ int win_dest_row(int n0) {
;     if (n0 < 5120) return n0;
;     if (n0 < 5152) return CDT + (n0 - 5120);
;     if (n0 < 7200) { const int c = n0 - 5152; return CCF + 256 * (c >> 7) + (c & 127); }
;     { const int c = n0 - 7200; return CCF + 256 * (c >> 7) + 128 + (c & 127); }
; }
; __global__ void __launch_bounds__(512, 2) mk_fwd(Args args) {
;     ...
;         for (int it = gw; it < n_items0; it += NGW) {
;             int r = it;
;             if (r < I_IN) { const int nblk = 9248 / 32, kb = r / nblk, nb = r % nblk; p0_transpose_item(w_in, DM, 9248, WinT, 64 * kb, 32 * nb, win_dest_row(32 * nb), scr, lane); continue; } r -= I_IN;
.Lp0t_loop:
	s_cmpk_lt_u32 s11, 14384
	s_cbranch_scc0 .Lp0t_last
	s_cmpk_lt_u32 s11, 9248
	s_cbranch_scc0 .Lp0t_main_notin
	s_mul_hi_u32 s40, s11, 14861479
	s_mul_i32 s42, s40, 289
	s_sub_u32 s41, s11, s42
	s_mul_i32 s42, s40, 2367488
	s_lshl_b32 s43, s41, 7
	s_add_u32 s42, s42, s43
	s_add_u32 s26, s12, s42
	s_addc_u32 s27, s13, 0
	s_mov_b32 s28, 36992
	s_lshl_b32 s45, s41, 5
	s_mov_b32 s46, s45
	s_cmpk_lt_u32 s45, 5120
	s_cbranch_scc1 .Lp0t_main_drow_done
	s_movk_i32 s46, 9216
	s_cmpk_lt_u32 s45, 5152
	s_cbranch_scc1 .Lp0t_main_drow_done
	s_sub_u32 s47, s45, 5152
	s_movk_i32 s43, 5120
	s_cmpk_lt_u32 s45, 7200
	s_cbranch_scc1 .Lp0t_main_drow_cf
	s_sub_u32 s47, s45, 7200
	s_movk_i32 s43, 5248

; #define LAS __attribute__((address_space(3)))
; __device__ __forceinline__ unsigned pk2(float lo, float hi) { unsigned r; asm("v_cvt_pk_bf16_f32 %0, %1, %2" : "=v"(r) : "v"(lo), "v"(hi)); return r; }
; __device__ __forceinline__ void p0_transpose_item(const float* W, int K, int N, bf16_t* WT, int k0, int n0, int drow0, LAS float* scr, int lane, const float* kscale = nullptr) {
;     const float ks = kscale ? kscale[k0 + lane] : 1.f;
; #pragma unroll 8
;     for (int i = 0; i < 32; ++i) { const int kk = 2 * i + (lane >> 5); scr[kk * 33 + (lane & 31)] = W[(size_t)(k0 + kk) * N + n0 + (lane & 31)] * __shfl(ks, kk); }
;     asm volatile("s_waitcnt lgkmcnt(0)" ::: "memory");
;     const int c = lane & 7;
; #pragma unroll
;     for (int j = 0; j < 4; ++j) { const int n = (lane >> 3) + 8 * j; const LAS float* s = scr + (8 * c) * 33 + n;
;         u32x4 o; o.x = pk2(s[0 * 33], s[1 * 33]); o.y = pk2(s[2 * 33], s[3 * 33]); o.z = pk2(s[4 * 33], s[5 * 33]); o.w = pk2(s[6 * 33], s[7 * 33]);
;         *(u32x4*)(WT + (size_t)(drow0 + n) * K + k0 + 8 * c) = o; }
;     asm volatile("s_waitcnt lgkmcnt(0)" ::: "memory");
.Lp0t_main_scaled:
	global_load_dwordx4 v[40:43], v20, s[26:27] nt
	s_add_u32 s26, s26, s29
	s_addc_u32 s27, s27, 0
	global_load_dwordx4 v[44:47], v20, s[26:27] nt
	s_add_u32 s26, s26, s29
	s_addc_u32 s27, s27, 0
	global_load_dwordx4 v[48:51], v20, s[26:27] nt
	s_add_u32 s26, s26, s29
	s_addc_u32 s27, s27, 0
	global_load_dwordx4 v[52:55], v20, s[26:27] nt
	s_add_u32 s26, s26, s29
	s_addc_u32 s27, s27, 0
	global_load_dwordx4 v[56:59], v20, s[26:27] nt
	s_add_u32 s26, s26, s29
	s_addc_u32 s27, s27, 0
	global_load_dwordx4 v[60:63], v20, s[26:27] nt
	s_add_u32 s26, s26, s29
	s_addc_u32 s27, s27, 0
	global_load_dwordx4 v[64:67], v20, s[26:27] nt
	s_add_u32 s26, s26, s29
	s_addc_u32 s27, s27, 0
	global_load_dwordx4 v[68:71], v20, s[26:27] nt
	ds_read2_b32 v[72:73], v16 offset0:0 offset1:32
	ds_read2_b32 v[74:75], v16 offset0:64 offset1:96
	ds_read2_b32 v[76:77], v16 offset0:128 offset1:160
	ds_read2_b32 v[78:79], v16 offset0:192 offset1:224
	ds_read2_b32 v[80:81], v17 offset0:0 offset1:32
	ds_read2_b32 v[82:83], v17 offset0:64 offset1:96
	ds_read2_b32 v[84:85], v17 offset0:128 offset1:160
	ds_read2_b32 v[86:87], v17 offset0:192 offset1:224
	ds_read2_b32 v[88:89], v18 offset0:0 offset1:32
	ds_read2_b32 v[90:91], v18 offset0:64 offset1:96
	ds_read2_b32 v[92:93], v18 offset0:128 offset1:160
	ds_read2_b32 v[94:95], v18 offset0:192 offset1:224
	v_mad_u32_u24 v21, v4, s38, v5
	s_lshl_b32 s39, s38, 3
	s_waitcnt lgkmcnt(8)
	ds_read2_b32 v[96:97], v19 offset0:0 offset1:32
	ds_read2_b32 v[98:99], v19 offset0:64 offset1:96
	ds_read2_b32 v[100:101], v19 offset0:128 offset1:160
	ds_read2_b32 v[102:103], v19 offset0:192 offset1:224
	v_mul_f32_e32 v72, v72, v24
	v_mul_f32_e32 v73, v73, v25
	v_mul_f32_e32 v74, v74, v26
	v_mul_f32_e32 v75, v75, v27
	v_mul_f32_e32 v76, v76, v28
	v_mul_f32_e32 v77, v77, v29
	v_mul_f32_e32 v78, v78, v30
	v_mul_f32_e32 v79, v79, v31
	v_cvt_pk_bf16_f32 v72, v72, v73
	v_cvt_pk_bf16_f32 v73, v74, v75
	v_cvt_pk_bf16_f32 v74, v76, v77
	v_cvt_pk_bf16_f32 v75, v78, v79
	global_store_dwordx4 v21, v[72:75], s[36:37]
	s_add_u32 s36, s36, s39
	s_addc_u32 s37, s37, 0
	s_waitcnt lgkmcnt(8)
	v_mul_f32_e32 v80, v80, v24
	v_mul_f32_e32 v81, v81, v25
	v_mul_f32_e32 v82, v82, v26
	v_mul_f32_e32 v83, v83, v27
	v_mul_f32_e32 v84, v84, v28
	v_mul_f32_e32 v85, v85, v29
	v_mul_f32_e32 v86, v86, v30
	v_mul_f32_e32 v87, v87, v31
	v_cvt_pk_bf16_f32 v80, v80, v81
	v_cvt_pk_bf16_f32 v81, v82, v83
	v_cvt_pk_bf16_f32 v82, v84, v85
	v_cvt_pk_bf16_f32 v83, v86, v87
	global_store_dwordx4 v21, v[80:83], s[36:37]
	s_add_u32 s36, s36, s39
	s_addc_u32 s37, s37, 0
	s_waitcnt lgkmcnt(4)
	v_mul_f32_e32 v88, v88, v24
	v_mul_f32_e32 v89, v89, v25
	v_mul_f32_e32 v90, v90, v26
	v_mul_f32_e32 v91, v91, v27
	v_mul_f32_e32 v92, v92, v28
	v_mul_f32_e32 v93, v93, v29
	v_mul_f32_e32 v94, v94, v30
	v_mul_f32_e32 v95, v95, v31
	v_cvt_pk_bf16_f32 v88, v88, v89
	v_cvt_pk_bf16_f32 v89, v90, v91
	v_cvt_pk_bf16_f32 v90, v92, v93
	v_cvt_pk_bf16_f32 v91, v94, v95
	global_store_dwordx4 v21, v[88:91], s[36:37]
	s_add_u32 s36, s36, s39
	s_addc_u32 s37, s37, 0
	s_waitcnt lgkmcnt(0)
	v_mul_f32_e32 v96, v96, v24
	v_mul_f32_e32 v97, v97, v25
	v_mul_f32_e32 v98, v98, v26
	v_mul_f32_e32 v99, v99, v27
	v_mul_f32_e32 v100, v100, v28
	v_mul_f32_e32 v101, v101, v29
	v_mul_f32_e32 v102, v102, v30
	v_mul_f32_e32 v103, v103, v31
	v_cvt_pk_bf16_f32 v96, v96, v97
	v_cvt_pk_bf16_f32 v97, v98, v99
	v_cvt_pk_bf16_f32 v98, v100, v101
	v_cvt_pk_bf16_f32 v99, v102, v103
	global_store_dwordx4 v21, v[96:99], s[36:37]
	s_waitcnt vmcnt(4)
	ds_write_b128 v8, v[40:43] offset:0
	ds_write_b128 v9, v[44:47] offset:1024
	ds_write_b128 v10, v[48:51] offset:2048
	ds_write_b128 v11, v[52:55] offset:3072
	ds_write_b128 v12, v[56:59] offset:4096
	ds_write_b128 v13, v[60:63] offset:5120
	ds_write_b128 v14, v[64:67] offset:6144
	ds_write_b128 v15, v[68:71] offset:7168
	v_mov_b32_e32 v24, v32
	v_mov_b32_e32 v25, v33
	v_mov_b32_e32 v26, v34
	v_mov_b32_e32 v27, v35
	v_mov_b32_e32 v28, v36
	v_mov_b32_e32 v29, v37
	v_mov_b32_e32 v30, v38
	v_mov_b32_e32 v31, v39
	s_mov_b64 s[36:37], s[30:31]
	s_mov_b32 s38, s32
	s_waitcnt lgkmcnt(0)
	s_add_u32 s11, s11, s10
	s_branch .Lp0t_loop
; #define LAS __attribute__((address_space(3)))
; __device__ __forceinline__ unsigned pk2(float lo, float hi) { unsigned r; asm("v_cvt_pk_bf16_f32 %0, %1, %2" : "=v"(r) : "v"(lo), "v"(hi)); return r; }
; __device__ __forceinline__ void p0_transpose_item(const float* W, int K, int N, bf16_t* WT, int k0, int n0, int drow0, LAS float* scr, int lane, const float* kscale = nullptr) {
;     const float ks = kscale ? kscale[k0 + lane] : 1.f;
; #pragma unroll 8
;     for (int i = 0; i < 32; ++i) { const int kk = 2 * i + (lane >> 5); scr[kk * 33 + (lane & 31)] = W[(size_t)(k0 + kk) * N + n0 + (lane & 31)] * __shfl(ks, kk); }
;     asm volatile("s_waitcnt lgkmcnt(0)" ::: "memory");
;     const int c = lane & 7;
; #pragma unroll
;     for (int j = 0; j < 4; ++j) { const int n = (lane >> 3) + 8 * j; const LAS float* s = scr + (8 * c) * 33 + n;
;         u32x4 o; o.x = pk2(s[0 * 33], s[1 * 33]); o.y = pk2(s[2 * 33], s[3 * 33]); o.z = pk2(s[4 * 33], s[5 * 33]); o.w = pk2(s[6 * 33], s[7 * 33]);
;         *(u32x4*)(WT + (size_t)(drow0 + n) * K + k0 + 8 * c) = o; }
;     asm volatile("s_waitcnt lgkmcnt(0)" ::: "memory");
; __global__ void __launch_bounds__(512, 2) mk_fwd(Args args) {
;     ...
;         const int gr = (gw + NGW - (n_items0 % NGW)) % NGW;
;         for (int m = gr; m < MT; m += NGW) { const float* xr = (m < MP) ? x_prompt + (size_t)m * DM : x_sample + (size_t)(m - MP) * DM; rms_row_to_bf16(xr, norm_mix_w, XN + (size_t)m * DM, lane); }
.Lp0t_last:
	ds_read2_b32 v[72:73], v16 offset0:0 offset1:32
	ds_read2_b32 v[74:75], v16 offset0:64 offset1:96
	ds_read2_b32 v[76:77], v16 offset0:128 offset1:160
	ds_read2_b32 v[78:79], v16 offset0:192 offset1:224
	ds_read2_b32 v[80:81], v17 offset0:0 offset1:32
	ds_read2_b32 v[82:83], v17 offset0:64 offset1:96
	ds_read2_b32 v[84:85], v17 offset0:128 offset1:160
	ds_read2_b32 v[86:87], v17 offset0:192 offset1:224
	ds_read2_b32 v[88:89], v18 offset0:0 offset1:32
	ds_read2_b32 v[90:91], v18 offset0:64 offset1:96
	ds_read2_b32 v[92:93], v18 offset0:128 offset1:160
	ds_read2_b32 v[94:95], v18 offset0:192 offset1:224
	v_mad_u32_u24 v21, v4, s38, v5
	s_lshl_b32 s39, s38, 3
	s_waitcnt lgkmcnt(8)
	ds_read2_b32 v[96:97], v19 offset0:0 offset1:32
	ds_read2_b32 v[98:99], v19 offset0:64 offset1:96
	ds_read2_b32 v[100:101], v19 offset0:128 offset1:160
	ds_read2_b32 v[102:103], v19 offset0:192 offset1:224
	v_mul_f32_e32 v72, v72, v24
	v_mul_f32_e32 v73, v73, v25
	v_mul_f32_e32 v74, v74, v26
	v_mul_f32_e32 v75, v75, v27
	v_mul_f32_e32 v76, v76, v28
	v_mul_f32_e32 v77, v77, v29
	v_mul_f32_e32 v78, v78, v30
	v_mul_f32_e32 v79, v79, v31
	v_cvt_pk_bf16_f32 v72, v72, v73
	v_cvt_pk_bf16_f32 v73, v74, v75
	v_cvt_pk_bf16_f32 v74, v76, v77
	v_cvt_pk_bf16_f32 v75, v78, v79
	global_store_dwordx4 v21, v[72:75], s[36:37]
	s_add_u32 s36, s36, s39
	s_addc_u32 s37, s37, 0
	s_waitcnt lgkmcnt(8)
	v_mul_f32_e32 v80, v80, v24
	v_mul_f32_e32 v81, v81, v25
	v_mul_f32_e32 v82, v82, v26
	v_mul_f32_e32 v83, v83, v27
	v_mul_f32_e32 v84, v84, v28
	v_mul_f32_e32 v85, v85, v29
	v_mul_f32_e32 v86, v86, v30
	v_mul_f32_e32 v87, v87, v31
	v_cvt_pk_bf16_f32 v80, v80, v81
	v_cvt_pk_bf16_f32 v81, v82, v83
	v_cvt_pk_bf16_f32 v82, v84, v85
	v_cvt_pk_bf16_f32 v83, v86, v87
	global_store_dwordx4 v21, v[80:83], s[36:37]
	s_add_u32 s36, s36, s39
	s_addc_u32 s37, s37, 0
	s_waitcnt lgkmcnt(4)
	v_mul_f32_e32 v88, v88, v24
	v_mul_f32_e32 v89, v89, v25
	v_mul_f32_e32 v90, v90, v26
	v_mul_f32_e32 v91, v91, v27
	v_mul_f32_e32 v92, v92, v28
	v_mul_f32_e32 v93, v93, v29
	v_mul_f32_e32 v94, v94, v30
	v_mul_f32_e32 v95, v95, v31
	v_cvt_pk_bf16_f32 v88, v88, v89
	v_cvt_pk_bf16_f32 v89, v90, v91
	v_cvt_pk_bf16_f32 v90, v92, v93
	v_cvt_pk_bf16_f32 v91, v94, v95
	global_store_dwordx4 v21, v[88:91], s[36:37]
	s_add_u32 s36, s36, s39
	s_addc_u32 s37, s37, 0
	s_waitcnt lgkmcnt(0)
	v_mul_f32_e32 v96, v96, v24
	v_mul_f32_e32 v97, v97, v25
	v_mul_f32_e32 v98, v98, v26
	v_mul_f32_e32 v99, v99, v27
	v_mul_f32_e32 v100, v100, v28
	v_mul_f32_e32 v101, v101, v29
	v_mul_f32_e32 v102, v102, v30
	v_mul_f32_e32 v103, v103, v31
	v_cvt_pk_bf16_f32 v96, v96, v97
	v_cvt_pk_bf16_f32 v97, v98, v99
	v_cvt_pk_bf16_f32 v98, v100, v101
	v_cvt_pk_bf16_f32 v99, v102, v103
	global_store_dwordx4 v21, v[96:99], s[36:37]
.LBB0_54:
	s_abs_i32 s4, s10
	v_cvt_f32_u32_e32 v1, s4
	s_sub_i32 s5, 0, s4
	s_add_i32 s3, s3, s10
	v_rcp_iflag_f32_e32 v1, v1
	s_nop 0
	v_mul_f32_e32 v1, 0x4f7ffffe, v1
	v_cvt_u32_f32_e32 v1, v1
	s_nop 0
	v_readfirstlane_b32 s6, v1
	s_mul_i32 s5, s5, s6
	s_mul_hi_u32 s5, s6, s5
	s_add_i32 s6, s6, s5
	s_mul_hi_u32 s5, s6, 0x3830
	s_mul_i32 s5, s5, s4
	s_sub_i32 s5, 0x3830, s5
	s_sub_i32 s7, s5, s4
	s_cmp_ge_u32 s5, s4
	s_cselect_b32 s5, s7, s5
	s_sub_i32 s7, s5, s4
	s_cmp_ge_u32 s5, s4
	s_cselect_b32 s5, s7, s5
	s_sub_i32 s3, s3, s5
	s_ashr_i32 s5, s3, 31
	s_abs_i32 s3, s3
	s_mul_hi_u32 s6, s3, s6
	s_mul_i32 s6, s6, s4
	s_sub_i32 s3, s3, s6
	s_sub_i32 s6, s3, s4
	s_cmp_ge_u32 s3, s4
	s_cselect_b32 s3, s6, s3
	s_sub_i32 s6, s3, s4
	s_cmp_ge_u32 s3, s4
	s_cselect_b32 s3, s6, s3
	s_xor_b32 s3, s3, s5
	s_sub_i32 s4, s3, s5
	s_cmpk_gt_i32 s4, 0x21ff
	s_mov_b32 s7, 0
	s_cbranch_scc1 .LBB0_61
	s_load_dwordx2 s[12:13], s[8:9], 0x0
	s_load_dwordx2 s[14:15], s[8:9], 0x8
	s_load_dwordx2 s[16:17], s[8:9], 0x30
	s_load_dwordx2 s[18:19], s[8:9], 0xd0
	v_lshlrev_b32_e32 v4, 4, v3
	v_lshlrev_b32_e32 v5, 3, v3
	v_xor_b32_e32 v6, 1, v3
	v_lshlrev_b32_e32 v6, 2, v6
	v_xor_b32_e32 v7, 2, v3
	v_lshlrev_b32_e32 v7, 2, v7
	v_xor_b32_e32 v8, 4, v3
	v_lshlrev_b32_e32 v8, 2, v8
	v_xor_b32_e32 v9, 8, v3
	v_lshlrev_b32_e32 v9, 2, v9
	v_xor_b32_e32 v10, 16, v3
	v_lshlrev_b32_e32 v10, 2, v10
	v_xor_b32_e32 v11, 32, v3
	v_lshlrev_b32_e32 v11, 2, v11
	v_mov_b32_e32 v16, 0x3727c5ac
	s_waitcnt lgkmcnt(0)
	s_add_u32 s18, s18, 0x7580000
	s_addc_u32 s19, s19, 0
	global_load_dwordx4 v[40:43], v4, s[16:17] offset:0
	global_load_dwordx4 v[44:47], v4, s[16:17] offset:1024
	global_load_dwordx4 v[48:51], v4, s[16:17] offset:2048
	global_load_dwordx4 v[52:55], v4, s[16:17] offset:3072
	s_add_u32 s16, s16, 4096
	s_addc_u32 s17, s17, 0
	global_load_dwordx4 v[56:59], v4, s[16:17] offset:0
	global_load_dwordx4 v[60:63], v4, s[16:17] offset:1024
	global_load_dwordx4 v[64:67], v4, s[16:17] offset:2048
	global_load_dwordx4 v[68:71], v4, s[16:17] offset:3072
	s_cmpk_lt_u32 s4, 8192
	s_cselect_b32 s20, s12, s14
	s_cselect_b32 s21, s13, s15
	s_cselect_b32 s28, 0, 8192
	s_sub_u32 s28, s4, s28
	s_lshr_b32 s29, s28, 19
	s_lshl_b32 s28, s28, 13
	s_add_u32 s20, s20, s28
	s_addc_u32 s21, s21, s29
	global_load_dwordx4 v[72:75], v4, s[20:21] offset:0 nt
	global_load_dwordx4 v[76:79], v4, s[20:21] offset:1024 nt
	global_load_dwordx4 v[80:83], v4, s[20:21] offset:2048 nt
	global_load_dwordx4 v[84:87], v4, s[20:21] offset:3072 nt
	s_add_u32 s20, s20, 4096
	s_addc_u32 s21, s21, 0
	global_load_dwordx4 v[88:91], v4, s[20:21] offset:0 nt
	global_load_dwordx4 v[92:95], v4, s[20:21] offset:1024 nt
	global_load_dwordx4 v[96:99], v4, s[20:21] offset:2048 nt
	global_load_dwordx4 v[100:103], v4, s[20:21] offset:3072 nt
	s_mov_b32 s27, 0

; #define LAS __attribute__((address_space(3)))
; __device__ __forceinline__ unsigned pk2(float lo, float hi) { unsigned r; asm("v_cvt_pk_bf16_f32 %0, %1, %2" : "=v"(r) : "v"(lo), "v"(hi)); return r; }
; #define LDS_BARRIER() do { asm volatile("s_waitcnt lgkmcnt(0)" ::: "memory"); __builtin_amdgcn_s_barrier(); asm volatile("" ::: "memory"); } while (0)
; #define MFMA16(a, b, c) __builtin_amdgcn_mfma_f32_16x16x32_bf16((a), (b), (c), 0, 0, 0)
; __device__ __forceinline__ void ssd_prompt(LAS unsigned char* lds, int b, int h, const bf16_t* XBC, const float* CS, const bf16_t* XT1, const bf16_t* XT2, const bf16_t* BT, bf16_t* MIX, float* p_ssm) {
;     ...
;         { const float dl = __expf(cs_last);
; #pragma unroll
;           for (int pt = 0; pt < 4; ++pt) hacc[pt] *= dl; }
; #pragma unroll
;         for (int ks = 0; ks < 4; ++ks) { const bf16x8 bb = *(const LAS bf16x8*)(BTs + (16 * w + fr) * LDP + ks * 32 + fq * 8);
; #pragma unroll
;             for (int pt = 0; pt < 4; ++pt) { const bf16x8 aa = *(const LAS bf16x8*)(X2s + (16 * pt + fr) * LDP + ks * 32 + fq * 8); hacc[pt] = MFMA16(bb, aa, hacc[pt]); } }
;         LDS_BARRIER();
; #pragma unroll
;         for (int pt = 0; pt < 4; ++pt) { u32x2 pk; pk.x = pk2(hacc[pt][0], hacc[pt][1]); pk.y = pk2(hacc[pt][2], hacc[pt][3]);
;             *(LAS u32x2*)(Hs + (16 * pt + fr) * LDP + 16 * w + 4 * fq) = pk; }
.LBB0_448:
	v_ashrrev_i32_e32 v133, 31, v132
	v_lshlrev_b64 v[132:133], 13, v[132:133]
	v_lshl_add_u64 v[132:133], v[106:107], 0, v[132:133]
	v_cvt_pk_bf16_f32 v80, v80, v81
	v_cvt_pk_bf16_f32 v81, v82, v83
	global_store_dwordx2 v[132:133], v[80:81], off
	v_cvt_pk_bf16_f32 v80, v84, v85
	v_cvt_pk_bf16_f32 v81, v86, v87
	global_store_dwordx2 v[132:133], v[80:81], off offset:32
	v_cvt_pk_bf16_f32 v80, v88, v89
	v_cvt_pk_bf16_f32 v81, v90, v91
	global_store_dwordx2 v[132:133], v[80:81], off offset:64
	v_cvt_pk_bf16_f32 v80, v92, v93
	v_cvt_pk_bf16_f32 v81, v94, v95
	global_store_dwordx2 v[132:133], v[80:81], off offset:96
	v_mul_f32_e32 v80, 0x3fb8aa3b, v163
	v_exp_f32_e32 v80, v80
	s_addk_i32 s17, 0x200
	s_addk_i32 s16, 0x80
	s_waitcnt vmcnt(7)
	v_mov_b64_e32 v[90:91], v[54:55]
	v_pk_mul_f32 v[66:67], v[66:67], v[80:81] op_sel_hi:[1,0]
	v_pk_mul_f32 v[64:65], v[64:65], v[80:81] op_sel_hi:[1,0]
	v_pk_mul_f32 v[70:71], v[70:71], v[80:81] op_sel_hi:[1,0]
	v_pk_mul_f32 v[68:69], v[68:69], v[80:81] op_sel_hi:[1,0]
	v_pk_mul_f32 v[74:75], v[74:75], v[80:81] op_sel_hi:[1,0]
	v_pk_mul_f32 v[72:73], v[72:73], v[80:81] op_sel_hi:[1,0]
	v_pk_mul_f32 v[78:79], v[78:79], v[80:81] op_sel_hi:[1,0]
	v_pk_mul_f32 v[76:77], v[76:77], v[80:81] op_sel_hi:[1,0]
	ds_read_b128 v[80:83], v108 offset:34816
	ds_read_b128 v[176:179], v160
	ds_read_b128 v[180:183], v160 offset:4352
	ds_read_b128 v[184:187], v160 offset:8704
	ds_read_b128 v[188:191], v160 offset:13056
	ds_read_b128 v[84:87], v108 offset:34880
	ds_read_b128 v[192:195], v160 offset:64
	ds_read_b128 v[196:199], v160 offset:4416
	ds_read_b128 v[200:203], v160 offset:8768
	ds_read_b128 v[204:207], v160 offset:13120
	ds_read_b128 v[244:247], v108 offset:34944
	ds_read_b128 v[208:211], v160 offset:128
	ds_read_b128 v[216:219], v160 offset:4480
	ds_read_b128 v[220:223], v160 offset:8832
	ds_read_b128 v[224:227], v160 offset:13184
	s_waitcnt vmcnt(5)
	v_mov_b64_e32 v[94:95], v[62:63]
	v_lshl_add_u64 v[124:125], v[124:125], 0, s[92:93]
	v_lshl_add_u64 v[126:127], v[126:127], 0, s[92:93]
	v_lshl_add_u64 v[128:129], v[128:129], 0, s[92:93]
	v_lshl_add_u64 v[130:131], v[130:131], 0, s[92:93]
	v_lshl_add_u64 v[114:115], v[114:115], 0, s[72:73]
	v_lshl_add_u64 v[116:117], v[116:117], 0, s[72:73]
	v_lshl_add_u64 v[118:119], v[118:119], 0, s[72:73]
	v_lshl_add_u64 v[120:121], v[120:121], 0, s[72:73]
	s_cmpk_lg_i32 s17, 0x2000
	v_mov_b64_e32 v[88:89], v[52:53]
	v_mov_b64_e32 v[92:93], v[60:61]
	s_waitcnt lgkmcnt(10)
	v_mfma_f32_16x16x32_bf16 v[64:67], v[80:83], v[176:179], v[64:67]
	v_mfma_f32_16x16x32_bf16 v[68:71], v[80:83], v[180:183], v[68:71]
	v_mfma_f32_16x16x32_bf16 v[72:75], v[80:83], v[184:187], v[72:75]
	v_mfma_f32_16x16x32_bf16 v[76:79], v[80:83], v[188:191], v[76:79]
	ds_read_b128 v[248:251], v108 offset:35008
	ds_read_b128 v[228:231], v160 offset:192
	ds_read_b128 v[232:235], v160 offset:4544
	ds_read_b128 v[236:239], v160 offset:8896
	ds_read_b128 v[240:243], v160 offset:13248
	s_waitcnt lgkmcnt(10)
	v_mfma_f32_16x16x32_bf16 v[64:67], v[84:87], v[192:195], v[64:67]
	v_mfma_f32_16x16x32_bf16 v[68:71], v[84:87], v[196:199], v[68:71]
	v_mfma_f32_16x16x32_bf16 v[72:75], v[84:87], v[200:203], v[72:75]
	v_mfma_f32_16x16x32_bf16 v[76:79], v[84:87], v[204:207], v[76:79]
	s_waitcnt lgkmcnt(5)
	v_mfma_f32_16x16x32_bf16 v[64:67], v[244:247], v[208:211], v[64:67]
	v_mfma_f32_16x16x32_bf16 v[68:71], v[244:247], v[216:219], v[68:71]
	v_mfma_f32_16x16x32_bf16 v[72:75], v[244:247], v[220:223], v[72:75]
	v_mfma_f32_16x16x32_bf16 v[76:79], v[244:247], v[224:227], v[76:79]
	s_waitcnt lgkmcnt(0)
	s_barrier
	v_mfma_f32_16x16x32_bf16 v[64:67], v[248:251], v[228:231], v[64:67]
	v_mfma_f32_16x16x32_bf16 v[68:71], v[248:251], v[232:235], v[68:71]
	v_mfma_f32_16x16x32_bf16 v[72:75], v[248:251], v[236:239], v[72:75]
	v_mfma_f32_16x16x32_bf16 v[76:79], v[248:251], v[240:243], v[76:79]
	s_nop 7
	s_nop 1
	v_cvt_pk_bf16_f32 v80, v64, v65
	v_cvt_pk_bf16_f32 v81, v66, v67
	ds_write_b64 v161, v[80:81]
	v_cvt_pk_bf16_f32 v80, v68, v69
	v_cvt_pk_bf16_f32 v81, v70, v71
	ds_write_b64 v161, v[80:81] offset:4352
	v_cvt_pk_bf16_f32 v80, v72, v73
	v_cvt_pk_bf16_f32 v81, v74, v75
	ds_write_b64 v161, v[80:81] offset:8704
	v_cvt_pk_bf16_f32 v80, v76, v77
	v_cvt_pk_bf16_f32 v81, v78, v79
	ds_write_b64 v161, v[80:81] offset:13056
	s_waitcnt vmcnt(4)
	v_mov_b64_e32 v[82:83], v[58:59]
	v_mov_b64_e32 v[86:87], v[50:51]
	v_mov_b64_e32 v[80:81], v[56:57]
	v_mov_b64_e32 v[84:85], v[48:49]
	s_cbranch_scc0 .LBB0_443

; #define LAS __attribute__((address_space(3)))
; #define MFMA16(a, b, c) __builtin_amdgcn_mfma_f32_16x16x32_bf16((a), (b), (c), 0, 0, 0)
; __device__ __forceinline__ void ssd_prompt(LAS unsigned char* lds, int b, int h, const bf16_t* XBC, const float* CS, const bf16_t* XT1, const bf16_t* XT2, const bf16_t* BT, bf16_t* MIX, float* p_ssm) {
;     ...
; #pragma unroll
;         for (int ks = 0; ks < 4; ++ks)
; #pragma unroll
;             for (int pt = 0; pt < 4; ++pt) { const bf16x8 bb = *(const LAS bf16x8*)(Hs + (16 * pt + fr) * LDP + ks * 32 + fq * 8); yacc[pt] = MFMA16(bb, afr[ks], yacc[pt]); }
;         { const float e = __expf(csi);
; #pragma unroll
;           for (int pt = 0; pt < 4; ++pt) yacc[pt] *= e; }
.LBB0_475:
	s_waitcnt lgkmcnt(0)
	ds_read_b128 v[176:179], v159
	ds_read_b128 v[180:183], v159 offset:4352
	ds_read_b128 v[184:187], v159 offset:8704
	ds_read_b128 v[188:191], v159 offset:13056
	ds_read_b128 v[192:195], v159 offset:64
	ds_read_b128 v[196:199], v159 offset:4416
	ds_read_b128 v[200:203], v159 offset:8768
	ds_read_b128 v[204:207], v159 offset:13120
	ds_read_b128 v[208:211], v159 offset:128
	ds_read_b128 v[216:219], v159 offset:4480
	ds_read_b128 v[220:223], v159 offset:8832
	ds_read_b128 v[224:227], v159 offset:13184
	s_andn2_b64 vcc, exec, s[8:9]
	s_waitcnt lgkmcnt(8)
	v_mfma_f32_16x16x32_bf16 v[134:137], v[176:179], v[92:95], 0
	v_mfma_f32_16x16x32_bf16 v[138:141], v[180:183], v[92:95], 0
	v_mfma_f32_16x16x32_bf16 v[142:145], v[184:187], v[92:95], 0
	v_mfma_f32_16x16x32_bf16 v[146:149], v[188:191], v[92:95], 0
	ds_read_b128 v[228:231], v159 offset:192
	ds_read_b128 v[232:235], v159 offset:4544
	ds_read_b128 v[236:239], v159 offset:8896
	ds_read_b128 v[240:243], v159 offset:13248
	s_waitcnt lgkmcnt(8)
	v_mfma_f32_16x16x32_bf16 v[134:137], v[192:195], v[88:91], v[134:137]
	v_mfma_f32_16x16x32_bf16 v[138:141], v[196:199], v[88:91], v[138:141]
	v_mfma_f32_16x16x32_bf16 v[142:145], v[200:203], v[88:91], v[142:145]
	v_mfma_f32_16x16x32_bf16 v[146:149], v[204:207], v[88:91], v[146:149]
	s_waitcnt lgkmcnt(4)
	v_mfma_f32_16x16x32_bf16 v[134:137], v[208:211], v[84:87], v[134:137]
	v_mfma_f32_16x16x32_bf16 v[138:141], v[216:219], v[84:87], v[138:141]
	v_mfma_f32_16x16x32_bf16 v[142:145], v[220:223], v[84:87], v[142:145]
	v_mfma_f32_16x16x32_bf16 v[146:149], v[224:227], v[84:87], v[146:149]
	s_waitcnt lgkmcnt(0)
	v_mfma_f32_16x16x32_bf16 v[134:137], v[228:231], v[80:83], v[134:137]
	v_mfma_f32_16x16x32_bf16 v[138:141], v[232:235], v[80:83], v[138:141]
	v_mfma_f32_16x16x32_bf16 v[142:145], v[236:239], v[80:83], v[142:145]
	v_mfma_f32_16x16x32_bf16 v[146:149], v[240:243], v[80:83], v[146:149]
	s_nop 7
	v_mul_f32_e32 v80, 0x3fb8aa3b, v133
	v_exp_f32_e32 v244, v80
	v_add_u32_e32 v133, v150, v100
	v_pk_mul_f32 v[82:83], v[244:245], v[136:137] op_sel_hi:[0,1]
	v_pk_mul_f32 v[80:81], v[244:245], v[134:135] op_sel_hi:[0,1]
	v_pk_mul_f32 v[86:87], v[244:245], v[140:141] op_sel_hi:[0,1]
	v_pk_mul_f32 v[84:85], v[244:245], v[138:139] op_sel_hi:[0,1]
	v_pk_mul_f32 v[90:91], v[244:245], v[144:145] op_sel_hi:[0,1]
	v_pk_mul_f32 v[88:89], v[244:245], v[142:143] op_sel_hi:[0,1]
	v_pk_mul_f32 v[94:95], v[244:245], v[148:149] op_sel_hi:[0,1]
	v_pk_mul_f32 v[92:93], v[244:245], v[146:147] op_sel_hi:[0,1]
	s_cbranch_vccz .LBB0_485
	s_andn2_b64 vcc, exec, s[10:11]
	s_cbranch_vccz .LBB0_486

; __global__ void __launch_bounds__(512, 2) mk_fwd(Args args) {
;     ...
;         for (int it = gw; it < n_items0; it += NGW) {
;             int r = it;
;             if (r < I_IN) { const int nblk = 9248 / 32, kb = r / nblk, nb = r % nblk; p0_transpose_item(w_in, DM, 9248, WinT, 64 * kb, 32 * nb, win_dest_row(32 * nb), scr, lane); continue; } r -= I_IN;
;             if (r < I_OUT) { const int nblk = DM / 32, kb = r / nblk, nb = r % nblk; p0_transpose_item(w_out, DMIX, DM, WoutT, 64 * kb, 32 * nb, 32 * nb, scr, lane); continue; } r -= I_OUT;
;             if (r < I_UP) { const int nblk = FF2 / 32, kb = r / nblk, nb = r % nblk; p0_transpose_item(w_up, DM, FF2, WupT, 64 * kb, 32 * nb, 32 * nb, scr, lane, norm_ffn_w); continue; } r -= I_UP;
;     ...
;         if (bx < npb) { if (psel != 2) for (int it = bx; it < NB * NH; it += npb) ssd_prompt(lds, it >> 5, it & 31, XBC, CS, XT1, XT2, BT, MIX, out + O_PSSM); }
;         else { if (psel != 1) ssd_sample_items(lds, bx - npb, G - npb, DB * NG, XBC, DT, a_log, state_ssm, MIX, out + O_SSSM);
;             if (psel == 0) for (int m = (bx - npb) * 8 + wave; m < MT; m += (G - npb) * 8) mix_finalize_conformer((size_t)m, MIX, CONVOUT, cf_ln_w, cf_ln_b, lane); }
.LBB0_491:
	v_writelane_b32 v254, s3, 0
	v_writelane_b32 v254, s4, 1
	v_writelane_b32 v254, s8, 2
	v_writelane_b32 v254, s9, 3
	v_writelane_b32 v254, s10, 4
	v_writelane_b32 v254, s11, 5
	v_writelane_b32 v254, s12, 6
	v_writelane_b32 v254, s13, 7
	v_writelane_b32 v254, s14, 8
	v_writelane_b32 v254, s15, 9
	v_writelane_b32 v254, s16, 10
	v_writelane_b32 v254, s17, 11
	v_writelane_b32 v254, s18, 12
	v_writelane_b32 v254, s19, 13
	v_writelane_b32 v254, s20, 14
	v_writelane_b32 v254, s21, 15
	v_writelane_b32 v254, s22, 16
	v_writelane_b32 v254, s23, 17
	v_writelane_b32 v254, s24, 18
	v_writelane_b32 v254, s25, 19
	v_writelane_b32 v254, s26, 20
	v_writelane_b32 v254, s27, 21
	v_writelane_b32 v254, s28, 22
	v_writelane_b32 v254, s29, 23
	v_writelane_b32 v254, s30, 24
	v_writelane_b32 v254, s31, 25
	v_writelane_b32 v254, s32, 26
	v_writelane_b32 v254, s33, 27
	v_writelane_b32 v254, s34, 28
	v_writelane_b32 v254, s35, 29
	v_writelane_b32 v254, s36, 30
	v_writelane_b32 v254, s37, 31
	v_writelane_b32 v254, s38, 32
	v_writelane_b32 v254, s39, 33
	v_writelane_b32 v254, s40, 34
	v_writelane_b32 v254, s41, 35
	v_writelane_b32 v254, s42, 36
	v_writelane_b32 v254, s43, 37
	v_writelane_b32 v254, s44, 38
	v_writelane_b32 v254, s45, 39
	v_writelane_b32 v254, s46, 40
	v_writelane_b32 v254, s47, 41
	s_cmpk_lt_u32 s2, 128
	s_cbranch_scc1 .Ltup3_skip
	s_mov_b64 s[8:9], s[96:97]
	v_and_b32_e32 v3, 63, v212
	v_readfirstlane_b32 s4, v212
	s_sub_u32 s3, s2, 128
	s_lshl_b32 s3, s3, 3
	s_lshr_b32 s4, s4, 6
	s_add_u32 s3, s3, s4
	s_add_u32 s11, s3, 14384
	s_sub_u32 s10, s94, 128
	s_lshl_b32 s10, s10, 3
	s_cmpk_lt_u32 s11, 17456
	s_cbranch_scc0 .Ltup3_skip
	s_load_dwordx2 s[12:13], s[8:9], 0x38
	s_load_dwordx2 s[14:15], s[8:9], 0x90
	s_load_dwordx2 s[16:17], s[8:9], 0xa0
	s_load_dwordx2 s[18:19], s[8:9], 0xb8
	s_load_dwordx2 s[20:21], s[8:9], 0x98
	s_load_dwordx2 s[22:23], s[8:9], 0xd0
	v_lshrrev_b32_e32 v4, 3, v3
	v_and_b32_e32 v7, 7, v3
	v_lshlrev_b32_e32 v5, 4, v7
	v_lshlrev_b32_e32 v6, 5, v7
	s_lshl_b32 s24, s4, 14
	v_lshl_add_u32 v16, v4, 7, s24
	v_xor_b32_e32 v8, 0, v7
	v_lshl_add_u32 v8, v8, 4, v16
	v_xor_b32_e32 v9, 1, v7
	v_lshl_add_u32 v9, v9, 4, v16
	v_xor_b32_e32 v10, 2, v7
	v_lshl_add_u32 v10, v10, 4, v16
	v_xor_b32_e32 v11, 3, v7
	v_lshl_add_u32 v11, v11, 4, v16
	v_xor_b32_e32 v12, 4, v7
	v_lshl_add_u32 v12, v12, 4, v16
	v_xor_b32_e32 v13, 5, v7
	v_lshl_add_u32 v13, v13, 4, v16
	v_xor_b32_e32 v14, 6, v7
	v_lshl_add_u32 v14, v14, 4, v16
	v_xor_b32_e32 v15, 7, v7
	v_lshl_add_u32 v15, v15, 4, v16
	v_lshlrev_b32_e32 v20, 2, v7
	v_lshl_add_u32 v21, v7, 10, s24
	v_add_u32_e32 v16, 0, v4
	v_xor_b32_e32 v16, v16, v20
	v_lshl_add_u32 v16, v16, 2, v21
	v_add_u32_e32 v17, 8, v4
	v_xor_b32_e32 v17, v17, v20
	v_lshl_add_u32 v17, v17, 2, v21
	v_add_u32_e32 v18, 16, v4
	v_xor_b32_e32 v18, v18, v20
	v_lshl_add_u32 v18, v18, 2, v21
	v_add_u32_e32 v19, 24, v4
	v_xor_b32_e32 v19, v19, v20
	v_lshl_add_u32 v19, v19, 2, v21
	s_waitcnt lgkmcnt(0)
	s_cmpk_lt_u32 s11, 9248
	s_cbranch_scc0 .Ltup3_pro_notin
	s_mul_hi_u32 s40, s11, 14861479
	s_mul_i32 s42, s40, 289
	s_sub_u32 s41, s11, s42
	s_mul_i32 s42, s40, 2367488
	s_lshl_b32 s43, s41, 7
	s_add_u32 s42, s42, s43
	s_add_u32 s26, s12, s42
	s_addc_u32 s27, s13, 0
	s_mov_b32 s28, 36992
	s_lshl_b32 s45, s41, 5
	s_mov_b32 s46, s45
	s_cmpk_lt_u32 s45, 5120
	s_cbranch_scc1 .Ltup3_pro_drow_done
	s_movk_i32 s46, 9216
	s_cmpk_lt_u32 s45, 5152
	s_cbranch_scc1 .Ltup3_pro_drow_done
	s_sub_u32 s47, s45, 5152
	s_movk_i32 s43, 5120
	s_cmpk_lt_u32 s45, 7200
	s_cbranch_scc1 .Ltup3_pro_drow_cf
	s_sub_u32 s47, s45, 7200
	s_movk_i32 s43, 5248

; __device__ __forceinline__ void xcd_barrier(const XcdBarrier& b) {
;     asm volatile("s_waitcnt vmcnt(0)" ::: "memory");
;     __syncthreads();
;     if (threadIdx.x == 0) {
;         unsigned* bar = b.bar;
;         __builtin_amdgcn_s_waitcnt(0);
;         unsigned nloc = b.st[0], nx = b.st[1];
;         if (nloc == 0u) { xcd_barrier_complete(bar, b.x, nloc, nx); b.st[0] = nloc; b.st[1] = nx; }
.Ltup3_skip:
	v_readlane_b32 s3, v254, 0
	v_readlane_b32 s4, v254, 1
	v_readlane_b32 s8, v254, 2
	v_readlane_b32 s9, v254, 3
	v_readlane_b32 s10, v254, 4
	v_readlane_b32 s11, v254, 5
	v_readlane_b32 s12, v254, 6
	v_readlane_b32 s13, v254, 7
	v_readlane_b32 s14, v254, 8
	v_readlane_b32 s15, v254, 9
	v_readlane_b32 s16, v254, 10
	v_readlane_b32 s17, v254, 11
	v_readlane_b32 s18, v254, 12
	v_readlane_b32 s19, v254, 13
	v_readlane_b32 s20, v254, 14
	v_readlane_b32 s21, v254, 15
	v_readlane_b32 s22, v254, 16
	v_readlane_b32 s23, v254, 17
	v_readlane_b32 s24, v254, 18
	v_readlane_b32 s25, v254, 19
	v_readlane_b32 s26, v254, 20
	v_readlane_b32 s27, v254, 21
	v_readlane_b32 s28, v254, 22
	v_readlane_b32 s29, v254, 23
	v_readlane_b32 s30, v254, 24
	v_readlane_b32 s31, v254, 25
	v_readlane_b32 s32, v254, 26
	v_readlane_b32 s33, v254, 27
	v_readlane_b32 s34, v254, 28
	v_readlane_b32 s35, v254, 29
	v_readlane_b32 s36, v254, 30
	v_readlane_b32 s37, v254, 31
	v_readlane_b32 s38, v254, 32
	v_readlane_b32 s39, v254, 33
	v_readlane_b32 s40, v254, 34
	v_readlane_b32 s41, v254, 35
	v_readlane_b32 s42, v254, 36
	v_readlane_b32 s43, v254, 37
	v_readlane_b32 s44, v254, 38
	v_readlane_b32 s45, v254, 39
	v_readlane_b32 s46, v254, 40
	v_readlane_b32 s47, v254, 41
	s_nop 4
	s_cmp_gt_i32 s89, 4
	s_cselect_b64 s[0:1], -1, 0
	s_and_b64 s[4:5], s[4:5], s[0:1]
	v_readlane_b32 s90, v253, 4
	s_andn2_b64 vcc, exec, s[4:5]
	v_readlane_b32 s91, v253, 5
	s_cbranch_vccnz .LBB0_545
	s_waitcnt vmcnt(0)
	s_waitcnt vmcnt(0) lgkmcnt(0)
	s_barrier
	s_and_saveexec_b64 s[4:5], s[90:91]
	s_cbranch_execz .LBB0_544
	s_add_i32 s3, 0, 0x23fc0
	v_mov_b32_e32 v0, s3
	s_waitcnt vmcnt(0) expcnt(0) lgkmcnt(0)
	ds_read_b32 v2, v0
	s_add_i32 s3, 0, 0x23fc4
	v_mov_b32_e32 v0, s3
	ds_read_b32 v0, v0
	s_waitcnt lgkmcnt(1)
	v_cmp_ne_u32_e32 vcc, 0, v2
	s_cbranch_vccnz .LBB0_508
	v_readlane_b32 s6, v253, 0
	v_readlane_b32 s7, v253, 1
	s_load_dwordx2 s[10:11], s[6:7], 0x4
	s_add_u32 s6, s74, 0x1000
	s_addc_u32 s7, s75, 0
	s_add_u32 s8, s74, 0x1100
	s_addc_u32 s9, s75, 0
	s_waitcnt lgkmcnt(0)
	s_mul_i32 s3, s10, s94
	s_add_u32 s10, s74, 0x1200
	s_mul_i32 s3, s3, s11
	s_addc_u32 s11, s75, 0
	s_add_u32 s12, s74, 0x1300
	s_addc_u32 s13, s75, 0
	s_mov_b32 s20, 1
	v_mov_b32_e32 v16, 0
	s_branch .LBB0_496
